# prologue weight transposes hand-written (eight 16-byte row loads of a 64x32 tile in flight, LDS tile transpose); U step uses one accumulator chain
# speedup vs baseline: 1.1285x; 1.0224x over previous
; #define FP8_LO(w) __builtin_amdgcn_cvt_pk_f32_fp8((int)(w), false)
; #define FP8_HI(w) __builtin_amdgcn_cvt_pk_f32_fp8((int)(w), true)
; DI float dot16p(const u32x4 xa, const u32x4 xb, const u32x4 w) {
;     const f32x2 a0 = FP8_LO(w.x), a1 = FP8_HI(w.x), a2 = FP8_LO(w.y), a3 = FP8_HI(w.y), a4 = FP8_LO(w.z), a5 = FP8_HI(w.z), a6 = FP8_LO(w.w), a7 = FP8_HI(w.w);
;     return (bflo(xa.x) * a0.x + bfhi(xa.x) * a0.y + bflo(xa.y) * a1.x + bfhi(xa.y) * a1.y) + (bflo(xa.z) * a2.x + bfhi(xa.z) * a2.y + bflo(xa.w) * a3.x + bfhi(xa.w) * a3.y)
;          + (bflo(xb.x) * a4.x + bfhi(xb.x) * a4.y + bflo(xb.y) * a5.x + bfhi(xb.y) * a5.y) + (bflo(xb.z) * a6.x + bfhi(xb.z) * a6.y + bflo(xb.w) * a7.x + bfhi(xb.w) * a7.y);
; DI void phase_peer_u(const Args& a, int layer, int ci) {
;     ...
;             for (int g8 = 0; g8 < 16; ++g8) {
;                 u32x4 nxt[8];
;                 if (g8 < 15) gat_loadhu(U, idA, idB, g8 + 1, lo16, nxt); else gat_loadhu(U, idAn, idBn, 0, lo16, nxt);
;                 const float c0 = dots4h(xa, xb, cur[0], cur[1], cur[2], cur[3], lane);
;                 const float c1 = dots4h(xa, xb, cur[4], cur[5], cur[6], cur[7], lane);
.Lpu_b0_nox:
	s_waitcnt lgkmcnt(0)
	s_add_u32 s44, s0, 2
	s_min_u32 s44, s44, 0xff
	s_bfe_u32 s45, s44, 0x10003
	s_lshl_b32 s45, s45, 12
	s_and_b32 s46, s44, 7
	s_lshl_b32 s46, s46, 6
	s_add_u32 s45, s45, s46
	v_add_u32_e32 v5, s45, v240
	ds_read_b128 v[72:75], v5
	ds_read_b128 v[76:79], v5 offset:16
	ds_read_b128 v[80:83], v5 offset:32
	ds_read_b128 v[84:87], v5 offset:48
	s_waitcnt vmcnt(15)
	v_cvt_pk_f32_fp8_e32 v[140:141], v8
	v_cvt_pk_f32_fp8_sdwa v[142:143], v8 src0_sel:WORD_1
	v_cvt_pk_f32_fp8_e32 v[144:145], v9
	v_cvt_pk_f32_fp8_sdwa v[146:147], v9 src0_sel:WORD_1
	v_pk_mul_f32 v[148:149], v[140:141], v[104:105]
	v_pk_fma_f32 v[148:149], v[142:143], v[106:107], v[148:149]
	v_pk_fma_f32 v[148:149], v[144:145], v[108:109], v[148:149]
	v_pk_fma_f32 v[148:149], v[146:147], v[110:111], v[148:149]
	v_cvt_pk_f32_fp8_e32 v[140:141], v10
	v_cvt_pk_f32_fp8_sdwa v[142:143], v10 src0_sel:WORD_1
	v_cvt_pk_f32_fp8_e32 v[144:145], v11
	v_cvt_pk_f32_fp8_sdwa v[146:147], v11 src0_sel:WORD_1
	v_pk_fma_f32 v[148:149], v[140:141], v[112:113], v[148:149]
	v_pk_fma_f32 v[148:149], v[142:143], v[114:115], v[148:149]
	v_pk_fma_f32 v[148:149], v[144:145], v[116:117], v[148:149]
	v_pk_fma_f32 v[148:149], v[146:147], v[118:119], v[148:149]
	v_add_f32_e32 v156, v148, v149
	v_lshl_add_u32 v3, v88, 7, v0
	global_load_dwordx4 v[8:11], v3, s[40:41]
	s_waitcnt vmcnt(15)
	v_cvt_pk_f32_fp8_e32 v[140:141], v12
	v_cvt_pk_f32_fp8_sdwa v[142:143], v12 src0_sel:WORD_1
	v_cvt_pk_f32_fp8_e32 v[144:145], v13
	v_cvt_pk_f32_fp8_sdwa v[146:147], v13 src0_sel:WORD_1
	v_pk_mul_f32 v[148:149], v[140:141], v[104:105]
	v_pk_fma_f32 v[148:149], v[142:143], v[106:107], v[148:149]
	v_pk_fma_f32 v[148:149], v[144:145], v[108:109], v[148:149]
	v_pk_fma_f32 v[148:149], v[146:147], v[110:111], v[148:149]
	v_cvt_pk_f32_fp8_e32 v[140:141], v14
	v_cvt_pk_f32_fp8_sdwa v[142:143], v14 src0_sel:WORD_1
	v_cvt_pk_f32_fp8_e32 v[144:145], v15
	v_cvt_pk_f32_fp8_sdwa v[146:147], v15 src0_sel:WORD_1
	v_pk_fma_f32 v[148:149], v[140:141], v[112:113], v[148:149]
	v_pk_fma_f32 v[148:149], v[142:143], v[114:115], v[148:149]
	v_pk_fma_f32 v[148:149], v[144:145], v[116:117], v[148:149]
	v_pk_fma_f32 v[148:149], v[146:147], v[118:119], v[148:149]
	v_add_f32_e32 v157, v148, v149
	v_lshl_add_u32 v4, v89, 7, v0
	global_load_dwordx4 v[12:15], v4, s[40:41]
	s_waitcnt vmcnt(15)
	v_cvt_pk_f32_fp8_e32 v[140:141], v16
	v_cvt_pk_f32_fp8_sdwa v[142:143], v16 src0_sel:WORD_1
	v_cvt_pk_f32_fp8_e32 v[144:145], v17
	v_cvt_pk_f32_fp8_sdwa v[146:147], v17 src0_sel:WORD_1
	v_pk_mul_f32 v[148:149], v[140:141], v[104:105]
	v_pk_fma_f32 v[148:149], v[142:143], v[106:107], v[148:149]
	v_pk_fma_f32 v[148:149], v[144:145], v[108:109], v[148:149]
	v_pk_fma_f32 v[148:149], v[146:147], v[110:111], v[148:149]
	v_cvt_pk_f32_fp8_e32 v[140:141], v18
	v_cvt_pk_f32_fp8_sdwa v[142:143], v18 src0_sel:WORD_1
	v_cvt_pk_f32_fp8_e32 v[144:145], v19
	v_cvt_pk_f32_fp8_sdwa v[146:147], v19 src0_sel:WORD_1
	v_pk_fma_f32 v[148:149], v[140:141], v[112:113], v[148:149]
	v_pk_fma_f32 v[148:149], v[142:143], v[114:115], v[148:149]
	v_pk_fma_f32 v[148:149], v[144:145], v[116:117], v[148:149]
	v_pk_fma_f32 v[148:149], v[146:147], v[118:119], v[148:149]
	v_add_f32_e32 v158, v148, v149
	v_lshl_add_u32 v3, v90, 7, v0
	global_load_dwordx4 v[16:19], v3, s[40:41]
	s_waitcnt vmcnt(15)
	v_cvt_pk_f32_fp8_e32 v[140:141], v20
	v_cvt_pk_f32_fp8_sdwa v[142:143], v20 src0_sel:WORD_1
	v_cvt_pk_f32_fp8_e32 v[144:145], v21
	v_cvt_pk_f32_fp8_sdwa v[146:147], v21 src0_sel:WORD_1
	v_pk_mul_f32 v[148:149], v[140:141], v[104:105]
	v_pk_fma_f32 v[148:149], v[142:143], v[106:107], v[148:149]
	v_pk_fma_f32 v[148:149], v[144:145], v[108:109], v[148:149]
	v_pk_fma_f32 v[148:149], v[146:147], v[110:111], v[148:149]
	v_cvt_pk_f32_fp8_e32 v[140:141], v22
	v_cvt_pk_f32_fp8_sdwa v[142:143], v22 src0_sel:WORD_1
	v_cvt_pk_f32_fp8_e32 v[144:145], v23
	v_cvt_pk_f32_fp8_sdwa v[146:147], v23 src0_sel:WORD_1
	v_pk_fma_f32 v[148:149], v[140:141], v[112:113], v[148:149]
	v_pk_fma_f32 v[148:149], v[142:143], v[114:115], v[148:149]
	v_pk_fma_f32 v[148:149], v[144:145], v[116:117], v[148:149]
	v_pk_fma_f32 v[148:149], v[146:147], v[118:119], v[148:149]
	v_add_f32_e32 v159, v148, v149
	v_lshl_add_u32 v4, v91, 7, v0
	global_load_dwordx4 v[20:23], v4, s[40:41]
	s_waitcnt vmcnt(15)
	v_cvt_pk_f32_fp8_e32 v[140:141], v24
	v_cvt_pk_f32_fp8_sdwa v[142:143], v24 src0_sel:WORD_1
	v_cvt_pk_f32_fp8_e32 v[144:145], v25
	v_cvt_pk_f32_fp8_sdwa v[146:147], v25 src0_sel:WORD_1
	v_pk_mul_f32 v[148:149], v[140:141], v[104:105]
	v_pk_fma_f32 v[148:149], v[142:143], v[106:107], v[148:149]
	v_pk_fma_f32 v[148:149], v[144:145], v[108:109], v[148:149]
	v_pk_fma_f32 v[148:149], v[146:147], v[110:111], v[148:149]
	v_cvt_pk_f32_fp8_e32 v[140:141], v26
	v_cvt_pk_f32_fp8_sdwa v[142:143], v26 src0_sel:WORD_1
	v_cvt_pk_f32_fp8_e32 v[144:145], v27
	v_cvt_pk_f32_fp8_sdwa v[146:147], v27 src0_sel:WORD_1
	v_pk_fma_f32 v[148:149], v[140:141], v[112:113], v[148:149]
	v_pk_fma_f32 v[148:149], v[142:143], v[114:115], v[148:149]
	v_pk_fma_f32 v[148:149], v[144:145], v[116:117], v[148:149]
	v_pk_fma_f32 v[148:149], v[146:147], v[118:119], v[148:149]
	v_add_f32_e32 v160, v148, v149
	v_lshl_add_u32 v3, v92, 7, v0
	global_load_dwordx4 v[24:27], v3, s[40:41]
	s_waitcnt vmcnt(15)
; #define FP8_LO(w) __builtin_amdgcn_cvt_pk_f32_fp8((int)(w), false)
; #define FP8_HI(w) __builtin_amdgcn_cvt_pk_f32_fp8((int)(w), true)
; DI float dot16p(const u32x4 xa, const u32x4 xb, const u32x4 w) {
;     const f32x2 a0 = FP8_LO(w.x), a1 = FP8_HI(w.x), a2 = FP8_LO(w.y), a3 = FP8_HI(w.y), a4 = FP8_LO(w.z), a5 = FP8_HI(w.z), a6 = FP8_LO(w.w), a7 = FP8_HI(w.w);
;     return (bflo(xa.x) * a0.x + bfhi(xa.x) * a0.y + bflo(xa.y) * a1.x + bfhi(xa.y) * a1.y) + (bflo(xa.z) * a2.x + bfhi(xa.z) * a2.y + bflo(xa.w) * a3.x + bfhi(xa.w) * a3.y)
;          + (bflo(xb.x) * a4.x + bfhi(xb.x) * a4.y + bflo(xb.y) * a5.x + bfhi(xb.y) * a5.y) + (bflo(xb.z) * a6.x + bfhi(xb.z) * a6.y + bflo(xb.w) * a7.x + bfhi(xb.w) * a7.y);
; DI void phase_peer_u(const Args& a, int layer, int ci) {
;     ...
;             for (int g8 = 0; g8 < 16; ++g8) {
;                 u32x4 nxt[8];
;                 if (g8 < 15) gat_loadhu(U, idA, idB, g8 + 1, lo16, nxt); else gat_loadhu(U, idAn, idBn, 0, lo16, nxt);
;                 const float c0 = dots4h(xa, xb, cur[0], cur[1], cur[2], cur[3], lane);
;                 const float c1 = dots4h(xa, xb, cur[4], cur[5], cur[6], cur[7], lane);
	v_cvt_pk_f32_fp8_e32 v[140:141], v28
	v_cvt_pk_f32_fp8_sdwa v[142:143], v28 src0_sel:WORD_1
	v_cvt_pk_f32_fp8_e32 v[144:145], v29
	v_cvt_pk_f32_fp8_sdwa v[146:147], v29 src0_sel:WORD_1
	v_pk_mul_f32 v[148:149], v[140:141], v[104:105]
	v_pk_fma_f32 v[148:149], v[142:143], v[106:107], v[148:149]
	v_pk_fma_f32 v[148:149], v[144:145], v[108:109], v[148:149]
	v_pk_fma_f32 v[148:149], v[146:147], v[110:111], v[148:149]
	v_cvt_pk_f32_fp8_e32 v[140:141], v30
	v_cvt_pk_f32_fp8_sdwa v[142:143], v30 src0_sel:WORD_1
	v_cvt_pk_f32_fp8_e32 v[144:145], v31
	v_cvt_pk_f32_fp8_sdwa v[146:147], v31 src0_sel:WORD_1
	v_pk_fma_f32 v[148:149], v[140:141], v[112:113], v[148:149]
	v_pk_fma_f32 v[148:149], v[142:143], v[114:115], v[148:149]
	v_pk_fma_f32 v[148:149], v[144:145], v[116:117], v[148:149]
	v_pk_fma_f32 v[148:149], v[146:147], v[118:119], v[148:149]
	v_add_f32_e32 v161, v148, v149
	v_lshl_add_u32 v4, v93, 7, v0
	global_load_dwordx4 v[28:31], v4, s[40:41]
	s_waitcnt vmcnt(15)
	v_cvt_pk_f32_fp8_e32 v[140:141], v32
	v_cvt_pk_f32_fp8_sdwa v[142:143], v32 src0_sel:WORD_1
	v_cvt_pk_f32_fp8_e32 v[144:145], v33
	v_cvt_pk_f32_fp8_sdwa v[146:147], v33 src0_sel:WORD_1
	v_pk_mul_f32 v[148:149], v[140:141], v[104:105]
	v_pk_fma_f32 v[148:149], v[142:143], v[106:107], v[148:149]
	v_pk_fma_f32 v[148:149], v[144:145], v[108:109], v[148:149]
	v_pk_fma_f32 v[148:149], v[146:147], v[110:111], v[148:149]
	v_cvt_pk_f32_fp8_e32 v[140:141], v34
	v_cvt_pk_f32_fp8_sdwa v[142:143], v34 src0_sel:WORD_1
	v_cvt_pk_f32_fp8_e32 v[144:145], v35
	v_cvt_pk_f32_fp8_sdwa v[146:147], v35 src0_sel:WORD_1
	v_pk_fma_f32 v[148:149], v[140:141], v[112:113], v[148:149]
	v_pk_fma_f32 v[148:149], v[142:143], v[114:115], v[148:149]
	v_pk_fma_f32 v[148:149], v[144:145], v[116:117], v[148:149]
	v_pk_fma_f32 v[148:149], v[146:147], v[118:119], v[148:149]
	v_add_f32_e32 v162, v148, v149
	v_lshl_add_u32 v3, v94, 7, v0
	global_load_dwordx4 v[32:35], v3, s[40:41]
	s_waitcnt vmcnt(15)
	v_cvt_pk_f32_fp8_e32 v[140:141], v36
	v_cvt_pk_f32_fp8_sdwa v[142:143], v36 src0_sel:WORD_1
	v_cvt_pk_f32_fp8_e32 v[144:145], v37
	v_cvt_pk_f32_fp8_sdwa v[146:147], v37 src0_sel:WORD_1
	v_pk_mul_f32 v[148:149], v[140:141], v[104:105]
	v_pk_fma_f32 v[148:149], v[142:143], v[106:107], v[148:149]
	v_pk_fma_f32 v[148:149], v[144:145], v[108:109], v[148:149]
	v_pk_fma_f32 v[148:149], v[146:147], v[110:111], v[148:149]
	v_cvt_pk_f32_fp8_e32 v[140:141], v38
	v_cvt_pk_f32_fp8_sdwa v[142:143], v38 src0_sel:WORD_1
	v_cvt_pk_f32_fp8_e32 v[144:145], v39
	v_cvt_pk_f32_fp8_sdwa v[146:147], v39 src0_sel:WORD_1
	v_pk_fma_f32 v[148:149], v[140:141], v[112:113], v[148:149]
	v_pk_fma_f32 v[148:149], v[142:143], v[114:115], v[148:149]
	v_pk_fma_f32 v[148:149], v[144:145], v[116:117], v[148:149]
	v_pk_fma_f32 v[148:149], v[146:147], v[118:119], v[148:149]
	v_add_f32_e32 v163, v148, v149
	v_lshl_add_u32 v4, v95, 7, v0
	global_load_dwordx4 v[36:39], v4, s[40:41]
	s_waitcnt vmcnt(15)
	v_cvt_pk_f32_fp8_e32 v[140:141], v40
	v_cvt_pk_f32_fp8_sdwa v[142:143], v40 src0_sel:WORD_1
	v_cvt_pk_f32_fp8_e32 v[144:145], v41
	v_cvt_pk_f32_fp8_sdwa v[146:147], v41 src0_sel:WORD_1
	v_pk_mul_f32 v[148:149], v[140:141], v[104:105]
	v_pk_fma_f32 v[148:149], v[142:143], v[106:107], v[148:149]
	v_pk_fma_f32 v[148:149], v[144:145], v[108:109], v[148:149]
	v_pk_fma_f32 v[148:149], v[146:147], v[110:111], v[148:149]
	v_cvt_pk_f32_fp8_e32 v[140:141], v42
	v_cvt_pk_f32_fp8_sdwa v[142:143], v42 src0_sel:WORD_1
	v_cvt_pk_f32_fp8_e32 v[144:145], v43
	v_cvt_pk_f32_fp8_sdwa v[146:147], v43 src0_sel:WORD_1
	v_pk_fma_f32 v[148:149], v[140:141], v[112:113], v[148:149]
	v_pk_fma_f32 v[148:149], v[142:143], v[114:115], v[148:149]
	v_pk_fma_f32 v[148:149], v[144:145], v[116:117], v[148:149]
	v_pk_fma_f32 v[148:149], v[146:147], v[118:119], v[148:149]
	v_add_f32_e32 v166, v148, v149
	v_lshl_add_u32 v3, v96, 7, v0
	global_load_dwordx4 v[40:43], v3, s[40:41]
	s_waitcnt vmcnt(15)
	v_cvt_pk_f32_fp8_e32 v[140:141], v44
	v_cvt_pk_f32_fp8_sdwa v[142:143], v44 src0_sel:WORD_1
	v_cvt_pk_f32_fp8_e32 v[144:145], v45
	v_cvt_pk_f32_fp8_sdwa v[146:147], v45 src0_sel:WORD_1
	v_pk_mul_f32 v[148:149], v[140:141], v[104:105]
	v_pk_fma_f32 v[148:149], v[142:143], v[106:107], v[148:149]
	v_pk_fma_f32 v[148:149], v[144:145], v[108:109], v[148:149]
	v_pk_fma_f32 v[148:149], v[146:147], v[110:111], v[148:149]
	v_cvt_pk_f32_fp8_e32 v[140:141], v46
	v_cvt_pk_f32_fp8_sdwa v[142:143], v46 src0_sel:WORD_1
	v_cvt_pk_f32_fp8_e32 v[144:145], v47
	v_cvt_pk_f32_fp8_sdwa v[146:147], v47 src0_sel:WORD_1
	v_pk_fma_f32 v[148:149], v[140:141], v[112:113], v[148:149]
	v_pk_fma_f32 v[148:149], v[142:143], v[114:115], v[148:149]
	v_pk_fma_f32 v[148:149], v[144:145], v[116:117], v[148:149]
	v_pk_fma_f32 v[148:149], v[146:147], v[118:119], v[148:149]
	v_add_f32_e32 v167, v148, v149
	v_lshl_add_u32 v4, v97, 7, v0
	global_load_dwordx4 v[44:47], v4, s[40:41]
	s_waitcnt vmcnt(15)
	v_cvt_pk_f32_fp8_e32 v[140:141], v48
	v_cvt_pk_f32_fp8_sdwa v[142:143], v48 src0_sel:WORD_1
	v_cvt_pk_f32_fp8_e32 v[144:145], v49
	v_cvt_pk_f32_fp8_sdwa v[146:147], v49 src0_sel:WORD_1
	v_pk_mul_f32 v[148:149], v[140:141], v[104:105]
	v_pk_fma_f32 v[148:149], v[142:143], v[106:107], v[148:149]
	v_pk_fma_f32 v[148:149], v[144:145], v[108:109], v[148:149]
	v_pk_fma_f32 v[148:149], v[146:147], v[110:111], v[148:149]
	v_cvt_pk_f32_fp8_e32 v[140:141], v50
	v_cvt_pk_f32_fp8_sdwa v[142:143], v50 src0_sel:WORD_1
	v_cvt_pk_f32_fp8_e32 v[144:145], v51
	v_cvt_pk_f32_fp8_sdwa v[146:147], v51 src0_sel:WORD_1
	v_pk_fma_f32 v[148:149], v[140:141], v[112:113], v[148:149]
	v_pk_fma_f32 v[148:149], v[142:143], v[114:115], v[148:149]
	v_pk_fma_f32 v[148:149], v[144:145], v[116:117], v[148:149]
	v_pk_fma_f32 v[148:149], v[146:147], v[118:119], v[148:149]
	v_add_f32_e32 v168, v148, v149
	v_lshl_add_u32 v3, v98, 7, v0
	global_load_dwordx4 v[48:51], v3, s[40:41]
	s_waitcnt vmcnt(15)
; #define FP8_LO(w) __builtin_amdgcn_cvt_pk_f32_fp8((int)(w), false)
; #define FP8_HI(w) __builtin_amdgcn_cvt_pk_f32_fp8((int)(w), true)
; DI float dot16p(const u32x4 xa, const u32x4 xb, const u32x4 w) {
;     const f32x2 a0 = FP8_LO(w.x), a1 = FP8_HI(w.x), a2 = FP8_LO(w.y), a3 = FP8_HI(w.y), a4 = FP8_LO(w.z), a5 = FP8_HI(w.z), a6 = FP8_LO(w.w), a7 = FP8_HI(w.w);
;     return (bflo(xa.x) * a0.x + bfhi(xa.x) * a0.y + bflo(xa.y) * a1.x + bfhi(xa.y) * a1.y) + (bflo(xa.z) * a2.x + bfhi(xa.z) * a2.y + bflo(xa.w) * a3.x + bfhi(xa.w) * a3.y)
;          + (bflo(xb.x) * a4.x + bfhi(xb.x) * a4.y + bflo(xb.y) * a5.x + bfhi(xb.y) * a5.y) + (bflo(xb.z) * a6.x + bfhi(xb.z) * a6.y + bflo(xb.w) * a7.x + bfhi(xb.w) * a7.y);
	v_cvt_pk_f32_fp8_e32 v[140:141], v52
	v_cvt_pk_f32_fp8_sdwa v[142:143], v52 src0_sel:WORD_1
	v_cvt_pk_f32_fp8_e32 v[144:145], v53
	v_cvt_pk_f32_fp8_sdwa v[146:147], v53 src0_sel:WORD_1
	v_pk_mul_f32 v[148:149], v[140:141], v[104:105]
	v_pk_fma_f32 v[148:149], v[142:143], v[106:107], v[148:149]
	v_pk_fma_f32 v[148:149], v[144:145], v[108:109], v[148:149]
	v_pk_fma_f32 v[148:149], v[146:147], v[110:111], v[148:149]
	v_cvt_pk_f32_fp8_e32 v[140:141], v54
	v_cvt_pk_f32_fp8_sdwa v[142:143], v54 src0_sel:WORD_1
	v_cvt_pk_f32_fp8_e32 v[144:145], v55
	v_cvt_pk_f32_fp8_sdwa v[146:147], v55 src0_sel:WORD_1
	v_pk_fma_f32 v[148:149], v[140:141], v[112:113], v[148:149]
	v_pk_fma_f32 v[148:149], v[142:143], v[114:115], v[148:149]
	v_pk_fma_f32 v[148:149], v[144:145], v[116:117], v[148:149]
	v_pk_fma_f32 v[148:149], v[146:147], v[118:119], v[148:149]
	v_add_f32_e32 v169, v148, v149
	v_lshl_add_u32 v4, v99, 7, v0
	global_load_dwordx4 v[52:55], v4, s[40:41]
	s_waitcnt vmcnt(15)
	v_cvt_pk_f32_fp8_e32 v[140:141], v56
	v_cvt_pk_f32_fp8_sdwa v[142:143], v56 src0_sel:WORD_1
	v_cvt_pk_f32_fp8_e32 v[144:145], v57
	v_cvt_pk_f32_fp8_sdwa v[146:147], v57 src0_sel:WORD_1
	v_pk_mul_f32 v[148:149], v[140:141], v[104:105]
	v_pk_fma_f32 v[148:149], v[142:143], v[106:107], v[148:149]
	v_pk_fma_f32 v[148:149], v[144:145], v[108:109], v[148:149]
	v_pk_fma_f32 v[148:149], v[146:147], v[110:111], v[148:149]
	v_cvt_pk_f32_fp8_e32 v[140:141], v58
	v_cvt_pk_f32_fp8_sdwa v[142:143], v58 src0_sel:WORD_1
	v_cvt_pk_f32_fp8_e32 v[144:145], v59
	v_cvt_pk_f32_fp8_sdwa v[146:147], v59 src0_sel:WORD_1
	v_pk_fma_f32 v[148:149], v[140:141], v[112:113], v[148:149]
	v_pk_fma_f32 v[148:149], v[142:143], v[114:115], v[148:149]
	v_pk_fma_f32 v[148:149], v[144:145], v[116:117], v[148:149]
	v_pk_fma_f32 v[148:149], v[146:147], v[118:119], v[148:149]
	v_add_f32_e32 v170, v148, v149
	v_lshl_add_u32 v3, v100, 7, v0
	global_load_dwordx4 v[56:59], v3, s[40:41]
	s_waitcnt vmcnt(15)
	v_cvt_pk_f32_fp8_e32 v[140:141], v60
	v_cvt_pk_f32_fp8_sdwa v[142:143], v60 src0_sel:WORD_1
	v_cvt_pk_f32_fp8_e32 v[144:145], v61
	v_cvt_pk_f32_fp8_sdwa v[146:147], v61 src0_sel:WORD_1
	v_pk_mul_f32 v[148:149], v[140:141], v[104:105]
	v_pk_fma_f32 v[148:149], v[142:143], v[106:107], v[148:149]
	v_pk_fma_f32 v[148:149], v[144:145], v[108:109], v[148:149]
	v_pk_fma_f32 v[148:149], v[146:147], v[110:111], v[148:149]
	v_cvt_pk_f32_fp8_e32 v[140:141], v62
	v_cvt_pk_f32_fp8_sdwa v[142:143], v62 src0_sel:WORD_1
	v_cvt_pk_f32_fp8_e32 v[144:145], v63
	v_cvt_pk_f32_fp8_sdwa v[146:147], v63 src0_sel:WORD_1
	v_pk_fma_f32 v[148:149], v[140:141], v[112:113], v[148:149]
	v_pk_fma_f32 v[148:149], v[142:143], v[114:115], v[148:149]
	v_pk_fma_f32 v[148:149], v[144:145], v[116:117], v[148:149]
	v_pk_fma_f32 v[148:149], v[146:147], v[118:119], v[148:149]
	v_add_f32_e32 v171, v148, v149
	v_lshl_add_u32 v4, v101, 7, v0
	global_load_dwordx4 v[60:63], v4, s[40:41]
	s_waitcnt vmcnt(15)
	v_cvt_pk_f32_fp8_e32 v[140:141], v64
	v_cvt_pk_f32_fp8_sdwa v[142:143], v64 src0_sel:WORD_1
	v_cvt_pk_f32_fp8_e32 v[144:145], v65
	v_cvt_pk_f32_fp8_sdwa v[146:147], v65 src0_sel:WORD_1
	v_pk_mul_f32 v[148:149], v[140:141], v[104:105]
	v_pk_fma_f32 v[148:149], v[142:143], v[106:107], v[148:149]
	v_pk_fma_f32 v[148:149], v[144:145], v[108:109], v[148:149]
	v_pk_fma_f32 v[148:149], v[146:147], v[110:111], v[148:149]
	v_cvt_pk_f32_fp8_e32 v[140:141], v66
	v_cvt_pk_f32_fp8_sdwa v[142:143], v66 src0_sel:WORD_1
	v_cvt_pk_f32_fp8_e32 v[144:145], v67
	v_cvt_pk_f32_fp8_sdwa v[146:147], v67 src0_sel:WORD_1
	v_pk_fma_f32 v[148:149], v[140:141], v[112:113], v[148:149]
	v_pk_fma_f32 v[148:149], v[142:143], v[114:115], v[148:149]
	v_pk_fma_f32 v[148:149], v[144:145], v[116:117], v[148:149]
	v_pk_fma_f32 v[148:149], v[146:147], v[118:119], v[148:149]
	v_add_f32_e32 v172, v148, v149
	v_lshl_add_u32 v3, v102, 7, v0
	global_load_dwordx4 v[64:67], v3, s[40:41]
	s_waitcnt vmcnt(15)
; #define FP8_LO(w) __builtin_amdgcn_cvt_pk_f32_fp8((int)(w), false)
; #define FP8_HI(w) __builtin_amdgcn_cvt_pk_f32_fp8((int)(w), true)
; DI float dot16p(const u32x4 xa, const u32x4 xb, const u32x4 w) {
;     const f32x2 a0 = FP8_LO(w.x), a1 = FP8_HI(w.x), a2 = FP8_LO(w.y), a3 = FP8_HI(w.y), a4 = FP8_LO(w.z), a5 = FP8_HI(w.z), a6 = FP8_LO(w.w), a7 = FP8_HI(w.w);
;     return (bflo(xa.x) * a0.x + bfhi(xa.x) * a0.y + bflo(xa.y) * a1.x + bfhi(xa.y) * a1.y) + (bflo(xa.z) * a2.x + bfhi(xa.z) * a2.y + bflo(xa.w) * a3.x + bfhi(xa.w) * a3.y)
;          + (bflo(xb.x) * a4.x + bfhi(xb.x) * a4.y + bflo(xb.y) * a5.x + bfhi(xb.y) * a5.y) + (bflo(xb.z) * a6.x + bfhi(xb.z) * a6.y + bflo(xb.w) * a7.x + bfhi(xb.w) * a7.y);
; DI float dots4h(const u32x4 xa, const u32x4 xb, const u32x4 b0, const u32x4 b1, const u32x4 b2, const u32x4 b3, int lane) {
;     const float d0 = dot16p(xa, xb, b0), d1 = dot16p(xa, xb, b1); __builtin_amdgcn_sched_barrier(0);
;     const float d2 = dot16p(xa, xb, b2), d3 = dot16p(xa, xb, b3); __builtin_amdgcn_sched_barrier(0);
;     const bool p1 = lane & 1, p2 = lane & 2;
;     const float b0s = (p1 ? d1 : d0) + __shfl_xor(p1 ? d0 : d1, 1);
;     const float b1s = (p1 ? d3 : d2) + __shfl_xor(p1 ? d2 : d3, 1);
;     float cs = (p2 ? b1s : b0s) + __shfl_xor(p2 ? b0s : b1s, 2);
;     cs += __shfl_xor(cs, 4); cs += __shfl_xor(cs, 8); cs += __shfl_xor(cs, 16); cs += __shfl_xor(cs, 32);
;     return cs;
	v_cvt_pk_f32_fp8_e32 v[140:141], v68
	v_cvt_pk_f32_fp8_sdwa v[142:143], v68 src0_sel:WORD_1
	v_cvt_pk_f32_fp8_e32 v[144:145], v69
	v_cvt_pk_f32_fp8_sdwa v[146:147], v69 src0_sel:WORD_1
	v_pk_mul_f32 v[148:149], v[140:141], v[104:105]
	v_pk_fma_f32 v[148:149], v[142:143], v[106:107], v[148:149]
	v_pk_fma_f32 v[148:149], v[144:145], v[108:109], v[148:149]
	v_pk_fma_f32 v[148:149], v[146:147], v[110:111], v[148:149]
	v_cvt_pk_f32_fp8_e32 v[140:141], v70
	v_cvt_pk_f32_fp8_sdwa v[142:143], v70 src0_sel:WORD_1
	v_cvt_pk_f32_fp8_e32 v[144:145], v71
	v_cvt_pk_f32_fp8_sdwa v[146:147], v71 src0_sel:WORD_1
	v_pk_fma_f32 v[148:149], v[140:141], v[112:113], v[148:149]
	v_pk_fma_f32 v[148:149], v[142:143], v[114:115], v[148:149]
	v_pk_fma_f32 v[148:149], v[144:145], v[116:117], v[148:149]
	v_pk_fma_f32 v[148:149], v[146:147], v[118:119], v[148:149]
	v_add_f32_e32 v173, v148, v149
	v_lshl_add_u32 v4, v103, 7, v0
	global_load_dwordx4 v[68:71], v4, s[40:41]
	v_cndmask_b32_e64 v152, v156, v157, s[34:35]
	v_cndmask_b32_e64 v174, v157, v156, s[34:35]
	v_cndmask_b32_e64 v153, v158, v159, s[34:35]
	v_cndmask_b32_e64 v175, v159, v158, s[34:35]
	v_cndmask_b32_e64 v154, v160, v161, s[34:35]
	v_cndmask_b32_e64 v176, v161, v160, s[34:35]
	v_cndmask_b32_e64 v155, v162, v163, s[34:35]
	v_cndmask_b32_e64 v177, v163, v162, s[34:35]
	v_add_f32_dpp v156, v174, v152 quad_perm:[1,0,3,2] row_mask:0xf bank_mask:0xf
	v_add_f32_dpp v157, v175, v153 quad_perm:[1,0,3,2] row_mask:0xf bank_mask:0xf
	v_add_f32_dpp v158, v176, v154 quad_perm:[1,0,3,2] row_mask:0xf bank_mask:0xf
	v_add_f32_dpp v159, v177, v155 quad_perm:[1,0,3,2] row_mask:0xf bank_mask:0xf
	v_cndmask_b32_e64 v152, v166, v167, s[34:35]
	v_cndmask_b32_e64 v174, v167, v166, s[34:35]
	v_cndmask_b32_e64 v153, v168, v169, s[34:35]
	v_cndmask_b32_e64 v175, v169, v168, s[34:35]
	v_cndmask_b32_e64 v154, v170, v171, s[34:35]
	v_cndmask_b32_e64 v176, v171, v170, s[34:35]
	v_cndmask_b32_e64 v155, v172, v173, s[34:35]
	v_cndmask_b32_e64 v177, v173, v172, s[34:35]
	v_add_f32_dpp v160, v174, v152 quad_perm:[1,0,3,2] row_mask:0xf bank_mask:0xf
	v_add_f32_dpp v161, v175, v153 quad_perm:[1,0,3,2] row_mask:0xf bank_mask:0xf
	v_add_f32_dpp v162, v176, v154 quad_perm:[1,0,3,2] row_mask:0xf bank_mask:0xf
	v_add_f32_dpp v163, v177, v155 quad_perm:[1,0,3,2] row_mask:0xf bank_mask:0xf
	v_cndmask_b32_e64 v152, v156, v157, s[48:49]
	v_cndmask_b32_e64 v174, v157, v156, s[48:49]
	v_cndmask_b32_e64 v153, v158, v159, s[48:49]
	v_cndmask_b32_e64 v175, v159, v158, s[48:49]
	v_cndmask_b32_e64 v154, v160, v161, s[48:49]
	v_cndmask_b32_e64 v176, v161, v160, s[48:49]
	v_cndmask_b32_e64 v155, v162, v163, s[48:49]
	v_cndmask_b32_e64 v177, v163, v162, s[48:49]
	v_add_f32_dpp v156, v174, v152 quad_perm:[2,3,0,1] row_mask:0xf bank_mask:0xf
	v_add_f32_dpp v157, v175, v153 quad_perm:[2,3,0,1] row_mask:0xf bank_mask:0xf
	v_add_f32_dpp v158, v176, v154 quad_perm:[2,3,0,1] row_mask:0xf bank_mask:0xf
	v_add_f32_dpp v159, v177, v155 quad_perm:[2,3,0,1] row_mask:0xf bank_mask:0xf
	v_mov_b64_e32 v[216:217], v[218:219]
	v_mov_b64_e32 v[218:219], v[220:221]
	v_mov_b64_e32 v[220:221], v[222:223]
	v_mov_b64_e32 v[222:223], v[224:225]
	v_mov_b64_e32 v[224:225], v[226:227]
	v_mov_b64_e32 v[226:227], v[232:233]
	v_mov_b64_e32 v[232:233], v[234:235]
	v_cndmask_b32_e64 v152, v156, v157, s[50:51]
	v_cndmask_b32_e64 v174, v157, v156, s[50:51]
	v_cndmask_b32_e64 v153, v158, v159, s[50:51]
	v_cndmask_b32_e64 v175, v159, v158, s[50:51]
	v_add_f32_dpp v234, v174, v152 row_shl:4 row_mask:0xf bank_mask:0x5
	v_add_f32_dpp v234, v174, v152 row_shr:4 row_mask:0xf bank_mask:0xa
	v_add_f32_dpp v235, v175, v153 row_shl:4 row_mask:0xf bank_mask:0x5
	v_add_f32_dpp v235, v175, v153 row_shr:4 row_mask:0xf bank_mask:0xa
	s_cmp_eq_u32 s47, 7
	s_cbranch_scc0 .Lpu_b0_nost
	s_bfe_u32 s45, s0, 0x40003
	s_lshl_b32 s45, s45, 20
	s_add_u32 s45, s45, s8
	s_lshr_b32 s46, s0, 7
	s_add_u32 s46, s46, s9
	s_lshl_b32 s46, s46, 24
	s_add_u32 s45, s45, s46
	s_add_u32 s45, s45, 0x20000000
	s_add_u32 s42, s98, s45
	s_addc_u32 s43, s99, 0
	global_store_dwordx4 v2, v[216:219], s[42:43]
	global_store_dwordx4 v2, v[220:223], s[42:43] offset:128
	global_store_dwordx4 v2, v[224:227], s[42:43] offset:256
	global_store_dwordx4 v2, v[232:235], s[42:43] offset:384
	v_lshlrev_b32_e32 v104, 16, v120
	v_and_b32_e32 v105, 0xffff0000, v120
	v_lshlrev_b32_e32 v106, 16, v121
	v_and_b32_e32 v107, 0xffff0000, v121
	v_lshlrev_b32_e32 v108, 16, v122
	v_and_b32_e32 v109, 0xffff0000, v122
	v_lshlrev_b32_e32 v110, 16, v123
	v_and_b32_e32 v111, 0xffff0000, v123
	v_lshlrev_b32_e32 v112, 16, v124
	v_and_b32_e32 v113, 0xffff0000, v124
	v_lshlrev_b32_e32 v114, 16, v125
	v_and_b32_e32 v115, 0xffff0000, v125
	v_lshlrev_b32_e32 v116, 16, v126
	v_and_b32_e32 v117, 0xffff0000, v126
	v_lshlrev_b32_e32 v118, 16, v127
	v_and_b32_e32 v119, 0xffff0000, v127

; #define FP8_LO(w) __builtin_amdgcn_cvt_pk_f32_fp8((int)(w), false)
; #define FP8_HI(w) __builtin_amdgcn_cvt_pk_f32_fp8((int)(w), true)
; DI float dot16p(const u32x4 xa, const u32x4 xb, const u32x4 w) {
;     const f32x2 a0 = FP8_LO(w.x), a1 = FP8_HI(w.x), a2 = FP8_LO(w.y), a3 = FP8_HI(w.y), a4 = FP8_LO(w.z), a5 = FP8_HI(w.z), a6 = FP8_LO(w.w), a7 = FP8_HI(w.w);
;     return (bflo(xa.x) * a0.x + bfhi(xa.x) * a0.y + bflo(xa.y) * a1.x + bfhi(xa.y) * a1.y) + (bflo(xa.z) * a2.x + bfhi(xa.z) * a2.y + bflo(xa.w) * a3.x + bfhi(xa.w) * a3.y)
;          + (bflo(xb.x) * a4.x + bfhi(xb.x) * a4.y + bflo(xb.y) * a5.x + bfhi(xb.y) * a5.y) + (bflo(xb.z) * a6.x + bfhi(xb.z) * a6.y + bflo(xb.w) * a7.x + bfhi(xb.w) * a7.y);
; DI void gat_loadhu(const unsigned char* base, int idlo, int idhi, int g8, unsigned lo16, u32x4 (&buf)[8]) {
;     const int ids = g8 < 8 ? idlo : idhi, e0 = (g8 & 7) * 8;
; #pragma unroll
;     for (int j = 0; j < 8; ++j) buf[j] = *(const u32x4*)(base + ((unsigned)__shfl(ids, e0 + j) * (unsigned)D + lo16));
.Lpu_b1_nox:
	s_waitcnt lgkmcnt(0)
	s_add_u32 s44, s0, 2
	s_min_u32 s44, s44, 0xff
	s_bfe_u32 s45, s44, 0x10003
	s_lshl_b32 s45, s45, 12
	s_and_b32 s46, s44, 7
	s_lshl_b32 s46, s46, 6
	s_add_u32 s45, s45, s46
	v_add_u32_e32 v5, s45, v240
	ds_read_b128 v[88:91], v5
	ds_read_b128 v[92:95], v5 offset:16
	ds_read_b128 v[96:99], v5 offset:32
	ds_read_b128 v[100:103], v5 offset:48
	s_waitcnt vmcnt(15)
	v_cvt_pk_f32_fp8_e32 v[140:141], v8
	v_cvt_pk_f32_fp8_sdwa v[142:143], v8 src0_sel:WORD_1
	v_cvt_pk_f32_fp8_e32 v[144:145], v9
	v_cvt_pk_f32_fp8_sdwa v[146:147], v9 src0_sel:WORD_1
	v_pk_mul_f32 v[148:149], v[140:141], v[104:105]
	v_pk_fma_f32 v[148:149], v[142:143], v[106:107], v[148:149]
	v_pk_fma_f32 v[148:149], v[144:145], v[108:109], v[148:149]
	v_pk_fma_f32 v[148:149], v[146:147], v[110:111], v[148:149]
	v_cvt_pk_f32_fp8_e32 v[140:141], v10
	v_cvt_pk_f32_fp8_sdwa v[142:143], v10 src0_sel:WORD_1
	v_cvt_pk_f32_fp8_e32 v[144:145], v11
	v_cvt_pk_f32_fp8_sdwa v[146:147], v11 src0_sel:WORD_1
	v_pk_fma_f32 v[148:149], v[140:141], v[112:113], v[148:149]
	v_pk_fma_f32 v[148:149], v[142:143], v[114:115], v[148:149]
	v_pk_fma_f32 v[148:149], v[144:145], v[116:117], v[148:149]
	v_pk_fma_f32 v[148:149], v[146:147], v[118:119], v[148:149]
	v_add_f32_e32 v156, v148, v149
	v_lshl_add_u32 v3, v72, 7, v0
	global_load_dwordx4 v[8:11], v3, s[40:41]
	s_waitcnt vmcnt(15)
	v_cvt_pk_f32_fp8_e32 v[140:141], v12
	v_cvt_pk_f32_fp8_sdwa v[142:143], v12 src0_sel:WORD_1
	v_cvt_pk_f32_fp8_e32 v[144:145], v13
	v_cvt_pk_f32_fp8_sdwa v[146:147], v13 src0_sel:WORD_1
	v_pk_mul_f32 v[148:149], v[140:141], v[104:105]
	v_pk_fma_f32 v[148:149], v[142:143], v[106:107], v[148:149]
	v_pk_fma_f32 v[148:149], v[144:145], v[108:109], v[148:149]
	v_pk_fma_f32 v[148:149], v[146:147], v[110:111], v[148:149]
	v_cvt_pk_f32_fp8_e32 v[140:141], v14
	v_cvt_pk_f32_fp8_sdwa v[142:143], v14 src0_sel:WORD_1
	v_cvt_pk_f32_fp8_e32 v[144:145], v15
	v_cvt_pk_f32_fp8_sdwa v[146:147], v15 src0_sel:WORD_1
	v_pk_fma_f32 v[148:149], v[140:141], v[112:113], v[148:149]
	v_pk_fma_f32 v[148:149], v[142:143], v[114:115], v[148:149]
	v_pk_fma_f32 v[148:149], v[144:145], v[116:117], v[148:149]
	v_pk_fma_f32 v[148:149], v[146:147], v[118:119], v[148:149]
	v_add_f32_e32 v157, v148, v149
	v_lshl_add_u32 v4, v73, 7, v0
	global_load_dwordx4 v[12:15], v4, s[40:41]
	s_waitcnt vmcnt(15)
	v_cvt_pk_f32_fp8_e32 v[140:141], v16
	v_cvt_pk_f32_fp8_sdwa v[142:143], v16 src0_sel:WORD_1
	v_cvt_pk_f32_fp8_e32 v[144:145], v17
	v_cvt_pk_f32_fp8_sdwa v[146:147], v17 src0_sel:WORD_1
	v_pk_mul_f32 v[148:149], v[140:141], v[104:105]
	v_pk_fma_f32 v[148:149], v[142:143], v[106:107], v[148:149]
	v_pk_fma_f32 v[148:149], v[144:145], v[108:109], v[148:149]
	v_pk_fma_f32 v[148:149], v[146:147], v[110:111], v[148:149]
	v_cvt_pk_f32_fp8_e32 v[140:141], v18
	v_cvt_pk_f32_fp8_sdwa v[142:143], v18 src0_sel:WORD_1
	v_cvt_pk_f32_fp8_e32 v[144:145], v19
	v_cvt_pk_f32_fp8_sdwa v[146:147], v19 src0_sel:WORD_1
	v_pk_fma_f32 v[148:149], v[140:141], v[112:113], v[148:149]
	v_pk_fma_f32 v[148:149], v[142:143], v[114:115], v[148:149]
	v_pk_fma_f32 v[148:149], v[144:145], v[116:117], v[148:149]
	v_pk_fma_f32 v[148:149], v[146:147], v[118:119], v[148:149]
	v_add_f32_e32 v158, v148, v149
	v_lshl_add_u32 v3, v74, 7, v0
	global_load_dwordx4 v[16:19], v3, s[40:41]
	s_waitcnt vmcnt(15)
	v_cvt_pk_f32_fp8_e32 v[140:141], v20
	v_cvt_pk_f32_fp8_sdwa v[142:143], v20 src0_sel:WORD_1
	v_cvt_pk_f32_fp8_e32 v[144:145], v21
	v_cvt_pk_f32_fp8_sdwa v[146:147], v21 src0_sel:WORD_1
	v_pk_mul_f32 v[148:149], v[140:141], v[104:105]
	v_pk_fma_f32 v[148:149], v[142:143], v[106:107], v[148:149]
	v_pk_fma_f32 v[148:149], v[144:145], v[108:109], v[148:149]
	v_pk_fma_f32 v[148:149], v[146:147], v[110:111], v[148:149]
	v_cvt_pk_f32_fp8_e32 v[140:141], v22
	v_cvt_pk_f32_fp8_sdwa v[142:143], v22 src0_sel:WORD_1
	v_cvt_pk_f32_fp8_e32 v[144:145], v23
	v_cvt_pk_f32_fp8_sdwa v[146:147], v23 src0_sel:WORD_1
	v_pk_fma_f32 v[148:149], v[140:141], v[112:113], v[148:149]
	v_pk_fma_f32 v[148:149], v[142:143], v[114:115], v[148:149]
	v_pk_fma_f32 v[148:149], v[144:145], v[116:117], v[148:149]
	v_pk_fma_f32 v[148:149], v[146:147], v[118:119], v[148:149]
	v_add_f32_e32 v159, v148, v149
	v_lshl_add_u32 v4, v75, 7, v0
	global_load_dwordx4 v[20:23], v4, s[40:41]
	s_waitcnt vmcnt(15)
	v_cvt_pk_f32_fp8_e32 v[140:141], v24
	v_cvt_pk_f32_fp8_sdwa v[142:143], v24 src0_sel:WORD_1
	v_cvt_pk_f32_fp8_e32 v[144:145], v25
	v_cvt_pk_f32_fp8_sdwa v[146:147], v25 src0_sel:WORD_1
	v_pk_mul_f32 v[148:149], v[140:141], v[104:105]
	v_pk_fma_f32 v[148:149], v[142:143], v[106:107], v[148:149]
	v_pk_fma_f32 v[148:149], v[144:145], v[108:109], v[148:149]
	v_pk_fma_f32 v[148:149], v[146:147], v[110:111], v[148:149]
	v_cvt_pk_f32_fp8_e32 v[140:141], v26
	v_cvt_pk_f32_fp8_sdwa v[142:143], v26 src0_sel:WORD_1
	v_cvt_pk_f32_fp8_e32 v[144:145], v27
	v_cvt_pk_f32_fp8_sdwa v[146:147], v27 src0_sel:WORD_1
	v_pk_fma_f32 v[148:149], v[140:141], v[112:113], v[148:149]
	v_pk_fma_f32 v[148:149], v[142:143], v[114:115], v[148:149]
	v_pk_fma_f32 v[148:149], v[144:145], v[116:117], v[148:149]
	v_pk_fma_f32 v[148:149], v[146:147], v[118:119], v[148:149]
	v_add_f32_e32 v160, v148, v149
	v_lshl_add_u32 v3, v76, 7, v0
	global_load_dwordx4 v[24:27], v3, s[40:41]
	s_waitcnt vmcnt(15)
; #define FP8_LO(w) __builtin_amdgcn_cvt_pk_f32_fp8((int)(w), false)
; #define FP8_HI(w) __builtin_amdgcn_cvt_pk_f32_fp8((int)(w), true)
; DI float dot16p(const u32x4 xa, const u32x4 xb, const u32x4 w) {
;     const f32x2 a0 = FP8_LO(w.x), a1 = FP8_HI(w.x), a2 = FP8_LO(w.y), a3 = FP8_HI(w.y), a4 = FP8_LO(w.z), a5 = FP8_HI(w.z), a6 = FP8_LO(w.w), a7 = FP8_HI(w.w);
;     return (bflo(xa.x) * a0.x + bfhi(xa.x) * a0.y + bflo(xa.y) * a1.x + bfhi(xa.y) * a1.y) + (bflo(xa.z) * a2.x + bfhi(xa.z) * a2.y + bflo(xa.w) * a3.x + bfhi(xa.w) * a3.y)
;          + (bflo(xb.x) * a4.x + bfhi(xb.x) * a4.y + bflo(xb.y) * a5.x + bfhi(xb.y) * a5.y) + (bflo(xb.z) * a6.x + bfhi(xb.z) * a6.y + bflo(xb.w) * a7.x + bfhi(xb.w) * a7.y);
	v_cvt_pk_f32_fp8_e32 v[140:141], v28
	v_cvt_pk_f32_fp8_sdwa v[142:143], v28 src0_sel:WORD_1
	v_cvt_pk_f32_fp8_e32 v[144:145], v29
	v_cvt_pk_f32_fp8_sdwa v[146:147], v29 src0_sel:WORD_1
	v_pk_mul_f32 v[148:149], v[140:141], v[104:105]
	v_pk_fma_f32 v[148:149], v[142:143], v[106:107], v[148:149]
	v_pk_fma_f32 v[148:149], v[144:145], v[108:109], v[148:149]
	v_pk_fma_f32 v[148:149], v[146:147], v[110:111], v[148:149]
	v_cvt_pk_f32_fp8_e32 v[140:141], v30
	v_cvt_pk_f32_fp8_sdwa v[142:143], v30 src0_sel:WORD_1
	v_cvt_pk_f32_fp8_e32 v[144:145], v31
	v_cvt_pk_f32_fp8_sdwa v[146:147], v31 src0_sel:WORD_1
	v_pk_fma_f32 v[148:149], v[140:141], v[112:113], v[148:149]
	v_pk_fma_f32 v[148:149], v[142:143], v[114:115], v[148:149]
	v_pk_fma_f32 v[148:149], v[144:145], v[116:117], v[148:149]
	v_pk_fma_f32 v[148:149], v[146:147], v[118:119], v[148:149]
	v_add_f32_e32 v161, v148, v149
	v_lshl_add_u32 v4, v77, 7, v0
	global_load_dwordx4 v[28:31], v4, s[40:41]
	s_waitcnt vmcnt(15)
	v_cvt_pk_f32_fp8_e32 v[140:141], v32
	v_cvt_pk_f32_fp8_sdwa v[142:143], v32 src0_sel:WORD_1
	v_cvt_pk_f32_fp8_e32 v[144:145], v33
	v_cvt_pk_f32_fp8_sdwa v[146:147], v33 src0_sel:WORD_1
	v_pk_mul_f32 v[148:149], v[140:141], v[104:105]
	v_pk_fma_f32 v[148:149], v[142:143], v[106:107], v[148:149]
	v_pk_fma_f32 v[148:149], v[144:145], v[108:109], v[148:149]
	v_pk_fma_f32 v[148:149], v[146:147], v[110:111], v[148:149]
	v_cvt_pk_f32_fp8_e32 v[140:141], v34
	v_cvt_pk_f32_fp8_sdwa v[142:143], v34 src0_sel:WORD_1
	v_cvt_pk_f32_fp8_e32 v[144:145], v35
	v_cvt_pk_f32_fp8_sdwa v[146:147], v35 src0_sel:WORD_1
	v_pk_fma_f32 v[148:149], v[140:141], v[112:113], v[148:149]
	v_pk_fma_f32 v[148:149], v[142:143], v[114:115], v[148:149]
	v_pk_fma_f32 v[148:149], v[144:145], v[116:117], v[148:149]
	v_pk_fma_f32 v[148:149], v[146:147], v[118:119], v[148:149]
	v_add_f32_e32 v162, v148, v149
	v_lshl_add_u32 v3, v78, 7, v0
	global_load_dwordx4 v[32:35], v3, s[40:41]
	s_waitcnt vmcnt(15)
	v_cvt_pk_f32_fp8_e32 v[140:141], v36
	v_cvt_pk_f32_fp8_sdwa v[142:143], v36 src0_sel:WORD_1
	v_cvt_pk_f32_fp8_e32 v[144:145], v37
	v_cvt_pk_f32_fp8_sdwa v[146:147], v37 src0_sel:WORD_1
	v_pk_mul_f32 v[148:149], v[140:141], v[104:105]
	v_pk_fma_f32 v[148:149], v[142:143], v[106:107], v[148:149]
	v_pk_fma_f32 v[148:149], v[144:145], v[108:109], v[148:149]
	v_pk_fma_f32 v[148:149], v[146:147], v[110:111], v[148:149]
	v_cvt_pk_f32_fp8_e32 v[140:141], v38
	v_cvt_pk_f32_fp8_sdwa v[142:143], v38 src0_sel:WORD_1
	v_cvt_pk_f32_fp8_e32 v[144:145], v39
	v_cvt_pk_f32_fp8_sdwa v[146:147], v39 src0_sel:WORD_1
	v_pk_fma_f32 v[148:149], v[140:141], v[112:113], v[148:149]
	v_pk_fma_f32 v[148:149], v[142:143], v[114:115], v[148:149]
	v_pk_fma_f32 v[148:149], v[144:145], v[116:117], v[148:149]
	v_pk_fma_f32 v[148:149], v[146:147], v[118:119], v[148:149]
	v_add_f32_e32 v163, v148, v149
	v_lshl_add_u32 v4, v79, 7, v0
	global_load_dwordx4 v[36:39], v4, s[40:41]
	s_waitcnt vmcnt(15)
	v_cvt_pk_f32_fp8_e32 v[140:141], v40
	v_cvt_pk_f32_fp8_sdwa v[142:143], v40 src0_sel:WORD_1
	v_cvt_pk_f32_fp8_e32 v[144:145], v41
	v_cvt_pk_f32_fp8_sdwa v[146:147], v41 src0_sel:WORD_1
	v_pk_mul_f32 v[148:149], v[140:141], v[104:105]
	v_pk_fma_f32 v[148:149], v[142:143], v[106:107], v[148:149]
	v_pk_fma_f32 v[148:149], v[144:145], v[108:109], v[148:149]
	v_pk_fma_f32 v[148:149], v[146:147], v[110:111], v[148:149]
	v_cvt_pk_f32_fp8_e32 v[140:141], v42
	v_cvt_pk_f32_fp8_sdwa v[142:143], v42 src0_sel:WORD_1
	v_cvt_pk_f32_fp8_e32 v[144:145], v43
	v_cvt_pk_f32_fp8_sdwa v[146:147], v43 src0_sel:WORD_1
	v_pk_fma_f32 v[148:149], v[140:141], v[112:113], v[148:149]
	v_pk_fma_f32 v[148:149], v[142:143], v[114:115], v[148:149]
	v_pk_fma_f32 v[148:149], v[144:145], v[116:117], v[148:149]
	v_pk_fma_f32 v[148:149], v[146:147], v[118:119], v[148:149]
	v_add_f32_e32 v166, v148, v149
	v_lshl_add_u32 v3, v80, 7, v0
	global_load_dwordx4 v[40:43], v3, s[40:41]
	s_waitcnt vmcnt(15)
	v_cvt_pk_f32_fp8_e32 v[140:141], v44
	v_cvt_pk_f32_fp8_sdwa v[142:143], v44 src0_sel:WORD_1
	v_cvt_pk_f32_fp8_e32 v[144:145], v45
	v_cvt_pk_f32_fp8_sdwa v[146:147], v45 src0_sel:WORD_1
	v_pk_mul_f32 v[148:149], v[140:141], v[104:105]
	v_pk_fma_f32 v[148:149], v[142:143], v[106:107], v[148:149]
	v_pk_fma_f32 v[148:149], v[144:145], v[108:109], v[148:149]
	v_pk_fma_f32 v[148:149], v[146:147], v[110:111], v[148:149]
	v_cvt_pk_f32_fp8_e32 v[140:141], v46
	v_cvt_pk_f32_fp8_sdwa v[142:143], v46 src0_sel:WORD_1
	v_cvt_pk_f32_fp8_e32 v[144:145], v47
	v_cvt_pk_f32_fp8_sdwa v[146:147], v47 src0_sel:WORD_1
	v_pk_fma_f32 v[148:149], v[140:141], v[112:113], v[148:149]
	v_pk_fma_f32 v[148:149], v[142:143], v[114:115], v[148:149]
	v_pk_fma_f32 v[148:149], v[144:145], v[116:117], v[148:149]
	v_pk_fma_f32 v[148:149], v[146:147], v[118:119], v[148:149]
	v_add_f32_e32 v167, v148, v149
	v_lshl_add_u32 v4, v81, 7, v0
	global_load_dwordx4 v[44:47], v4, s[40:41]
	s_waitcnt vmcnt(15)
	v_cvt_pk_f32_fp8_e32 v[140:141], v48
	v_cvt_pk_f32_fp8_sdwa v[142:143], v48 src0_sel:WORD_1
	v_cvt_pk_f32_fp8_e32 v[144:145], v49
	v_cvt_pk_f32_fp8_sdwa v[146:147], v49 src0_sel:WORD_1
	v_pk_mul_f32 v[148:149], v[140:141], v[104:105]
	v_pk_fma_f32 v[148:149], v[142:143], v[106:107], v[148:149]
	v_pk_fma_f32 v[148:149], v[144:145], v[108:109], v[148:149]
	v_pk_fma_f32 v[148:149], v[146:147], v[110:111], v[148:149]
	v_cvt_pk_f32_fp8_e32 v[140:141], v50
	v_cvt_pk_f32_fp8_sdwa v[142:143], v50 src0_sel:WORD_1
	v_cvt_pk_f32_fp8_e32 v[144:145], v51
	v_cvt_pk_f32_fp8_sdwa v[146:147], v51 src0_sel:WORD_1
	v_pk_fma_f32 v[148:149], v[140:141], v[112:113], v[148:149]
	v_pk_fma_f32 v[148:149], v[142:143], v[114:115], v[148:149]
	v_pk_fma_f32 v[148:149], v[144:145], v[116:117], v[148:149]
	v_pk_fma_f32 v[148:149], v[146:147], v[118:119], v[148:149]
	v_add_f32_e32 v168, v148, v149
	v_lshl_add_u32 v3, v82, 7, v0
	global_load_dwordx4 v[48:51], v3, s[40:41]
	s_waitcnt vmcnt(15)
; #define FP8_LO(w) __builtin_amdgcn_cvt_pk_f32_fp8((int)(w), false)
; #define FP8_HI(w) __builtin_amdgcn_cvt_pk_f32_fp8((int)(w), true)
; DI float dot16p(const u32x4 xa, const u32x4 xb, const u32x4 w) {
;     const f32x2 a0 = FP8_LO(w.x), a1 = FP8_HI(w.x), a2 = FP8_LO(w.y), a3 = FP8_HI(w.y), a4 = FP8_LO(w.z), a5 = FP8_HI(w.z), a6 = FP8_LO(w.w), a7 = FP8_HI(w.w);
;     return (bflo(xa.x) * a0.x + bfhi(xa.x) * a0.y + bflo(xa.y) * a1.x + bfhi(xa.y) * a1.y) + (bflo(xa.z) * a2.x + bfhi(xa.z) * a2.y + bflo(xa.w) * a3.x + bfhi(xa.w) * a3.y)
;          + (bflo(xb.x) * a4.x + bfhi(xb.x) * a4.y + bflo(xb.y) * a5.x + bfhi(xb.y) * a5.y) + (bflo(xb.z) * a6.x + bfhi(xb.z) * a6.y + bflo(xb.w) * a7.x + bfhi(xb.w) * a7.y);
	v_cvt_pk_f32_fp8_e32 v[140:141], v52
	v_cvt_pk_f32_fp8_sdwa v[142:143], v52 src0_sel:WORD_1
	v_cvt_pk_f32_fp8_e32 v[144:145], v53
	v_cvt_pk_f32_fp8_sdwa v[146:147], v53 src0_sel:WORD_1
	v_pk_mul_f32 v[148:149], v[140:141], v[104:105]
	v_pk_fma_f32 v[148:149], v[142:143], v[106:107], v[148:149]
	v_pk_fma_f32 v[148:149], v[144:145], v[108:109], v[148:149]
	v_pk_fma_f32 v[148:149], v[146:147], v[110:111], v[148:149]
	v_cvt_pk_f32_fp8_e32 v[140:141], v54
	v_cvt_pk_f32_fp8_sdwa v[142:143], v54 src0_sel:WORD_1
	v_cvt_pk_f32_fp8_e32 v[144:145], v55
	v_cvt_pk_f32_fp8_sdwa v[146:147], v55 src0_sel:WORD_1
	v_pk_fma_f32 v[148:149], v[140:141], v[112:113], v[148:149]
	v_pk_fma_f32 v[148:149], v[142:143], v[114:115], v[148:149]
	v_pk_fma_f32 v[148:149], v[144:145], v[116:117], v[148:149]
	v_pk_fma_f32 v[148:149], v[146:147], v[118:119], v[148:149]
	v_add_f32_e32 v169, v148, v149
	v_lshl_add_u32 v4, v83, 7, v0
	global_load_dwordx4 v[52:55], v4, s[40:41]
	s_waitcnt vmcnt(15)
	v_cvt_pk_f32_fp8_e32 v[140:141], v56
	v_cvt_pk_f32_fp8_sdwa v[142:143], v56 src0_sel:WORD_1
	v_cvt_pk_f32_fp8_e32 v[144:145], v57
	v_cvt_pk_f32_fp8_sdwa v[146:147], v57 src0_sel:WORD_1
	v_pk_mul_f32 v[148:149], v[140:141], v[104:105]
	v_pk_fma_f32 v[148:149], v[142:143], v[106:107], v[148:149]
	v_pk_fma_f32 v[148:149], v[144:145], v[108:109], v[148:149]
	v_pk_fma_f32 v[148:149], v[146:147], v[110:111], v[148:149]
	v_cvt_pk_f32_fp8_e32 v[140:141], v58
	v_cvt_pk_f32_fp8_sdwa v[142:143], v58 src0_sel:WORD_1
	v_cvt_pk_f32_fp8_e32 v[144:145], v59
	v_cvt_pk_f32_fp8_sdwa v[146:147], v59 src0_sel:WORD_1
	v_pk_fma_f32 v[148:149], v[140:141], v[112:113], v[148:149]
	v_pk_fma_f32 v[148:149], v[142:143], v[114:115], v[148:149]
	v_pk_fma_f32 v[148:149], v[144:145], v[116:117], v[148:149]
	v_pk_fma_f32 v[148:149], v[146:147], v[118:119], v[148:149]
	v_add_f32_e32 v170, v148, v149
	v_lshl_add_u32 v3, v84, 7, v0
	global_load_dwordx4 v[56:59], v3, s[40:41]
	s_waitcnt vmcnt(15)
	v_cvt_pk_f32_fp8_e32 v[140:141], v60
	v_cvt_pk_f32_fp8_sdwa v[142:143], v60 src0_sel:WORD_1
	v_cvt_pk_f32_fp8_e32 v[144:145], v61
	v_cvt_pk_f32_fp8_sdwa v[146:147], v61 src0_sel:WORD_1
	v_pk_mul_f32 v[148:149], v[140:141], v[104:105]
	v_pk_fma_f32 v[148:149], v[142:143], v[106:107], v[148:149]
	v_pk_fma_f32 v[148:149], v[144:145], v[108:109], v[148:149]
	v_pk_fma_f32 v[148:149], v[146:147], v[110:111], v[148:149]
	v_cvt_pk_f32_fp8_e32 v[140:141], v62
	v_cvt_pk_f32_fp8_sdwa v[142:143], v62 src0_sel:WORD_1
	v_cvt_pk_f32_fp8_e32 v[144:145], v63
	v_cvt_pk_f32_fp8_sdwa v[146:147], v63 src0_sel:WORD_1
	v_pk_fma_f32 v[148:149], v[140:141], v[112:113], v[148:149]
	v_pk_fma_f32 v[148:149], v[142:143], v[114:115], v[148:149]
	v_pk_fma_f32 v[148:149], v[144:145], v[116:117], v[148:149]
	v_pk_fma_f32 v[148:149], v[146:147], v[118:119], v[148:149]
	v_add_f32_e32 v171, v148, v149
	v_lshl_add_u32 v4, v85, 7, v0
	global_load_dwordx4 v[60:63], v4, s[40:41]
	s_waitcnt vmcnt(15)
	v_cvt_pk_f32_fp8_e32 v[140:141], v64
	v_cvt_pk_f32_fp8_sdwa v[142:143], v64 src0_sel:WORD_1
	v_cvt_pk_f32_fp8_e32 v[144:145], v65
	v_cvt_pk_f32_fp8_sdwa v[146:147], v65 src0_sel:WORD_1
	v_pk_mul_f32 v[148:149], v[140:141], v[104:105]
	v_pk_fma_f32 v[148:149], v[142:143], v[106:107], v[148:149]
	v_pk_fma_f32 v[148:149], v[144:145], v[108:109], v[148:149]
	v_pk_fma_f32 v[148:149], v[146:147], v[110:111], v[148:149]
	v_cvt_pk_f32_fp8_e32 v[140:141], v66
	v_cvt_pk_f32_fp8_sdwa v[142:143], v66 src0_sel:WORD_1
	v_cvt_pk_f32_fp8_e32 v[144:145], v67
	v_cvt_pk_f32_fp8_sdwa v[146:147], v67 src0_sel:WORD_1
	v_pk_fma_f32 v[148:149], v[140:141], v[112:113], v[148:149]
	v_pk_fma_f32 v[148:149], v[142:143], v[114:115], v[148:149]
	v_pk_fma_f32 v[148:149], v[144:145], v[116:117], v[148:149]
	v_pk_fma_f32 v[148:149], v[146:147], v[118:119], v[148:149]
	v_add_f32_e32 v172, v148, v149
	v_lshl_add_u32 v3, v86, 7, v0
	global_load_dwordx4 v[64:67], v3, s[40:41]
	s_waitcnt vmcnt(15)
; #define FP8_LO(w) __builtin_amdgcn_cvt_pk_f32_fp8((int)(w), false)
; #define FP8_HI(w) __builtin_amdgcn_cvt_pk_f32_fp8((int)(w), true)
; DI float dot16p(const u32x4 xa, const u32x4 xb, const u32x4 w) {
;     const f32x2 a0 = FP8_LO(w.x), a1 = FP8_HI(w.x), a2 = FP8_LO(w.y), a3 = FP8_HI(w.y), a4 = FP8_LO(w.z), a5 = FP8_HI(w.z), a6 = FP8_LO(w.w), a7 = FP8_HI(w.w);
;     return (bflo(xa.x) * a0.x + bfhi(xa.x) * a0.y + bflo(xa.y) * a1.x + bfhi(xa.y) * a1.y) + (bflo(xa.z) * a2.x + bfhi(xa.z) * a2.y + bflo(xa.w) * a3.x + bfhi(xa.w) * a3.y)
;          + (bflo(xb.x) * a4.x + bfhi(xb.x) * a4.y + bflo(xb.y) * a5.x + bfhi(xb.y) * a5.y) + (bflo(xb.z) * a6.x + bfhi(xb.z) * a6.y + bflo(xb.w) * a7.x + bfhi(xb.w) * a7.y);
; DI float dots4h(const u32x4 xa, const u32x4 xb, const u32x4 b0, const u32x4 b1, const u32x4 b2, const u32x4 b3, int lane) {
;     const float d0 = dot16p(xa, xb, b0), d1 = dot16p(xa, xb, b1); __builtin_amdgcn_sched_barrier(0);
;     const float d2 = dot16p(xa, xb, b2), d3 = dot16p(xa, xb, b3); __builtin_amdgcn_sched_barrier(0);
;     const bool p1 = lane & 1, p2 = lane & 2;
;     const float b0s = (p1 ? d1 : d0) + __shfl_xor(p1 ? d0 : d1, 1);
;     const float b1s = (p1 ? d3 : d2) + __shfl_xor(p1 ? d2 : d3, 1);
;     float cs = (p2 ? b1s : b0s) + __shfl_xor(p2 ? b0s : b1s, 2);
;     cs += __shfl_xor(cs, 4); cs += __shfl_xor(cs, 8); cs += __shfl_xor(cs, 16); cs += __shfl_xor(cs, 32);
;     return cs;
	v_cvt_pk_f32_fp8_e32 v[140:141], v68
	v_cvt_pk_f32_fp8_sdwa v[142:143], v68 src0_sel:WORD_1
	v_cvt_pk_f32_fp8_e32 v[144:145], v69
	v_cvt_pk_f32_fp8_sdwa v[146:147], v69 src0_sel:WORD_1
	v_pk_mul_f32 v[148:149], v[140:141], v[104:105]
	v_pk_fma_f32 v[148:149], v[142:143], v[106:107], v[148:149]
	v_pk_fma_f32 v[148:149], v[144:145], v[108:109], v[148:149]
	v_pk_fma_f32 v[148:149], v[146:147], v[110:111], v[148:149]
	v_cvt_pk_f32_fp8_e32 v[140:141], v70
	v_cvt_pk_f32_fp8_sdwa v[142:143], v70 src0_sel:WORD_1
	v_cvt_pk_f32_fp8_e32 v[144:145], v71
	v_cvt_pk_f32_fp8_sdwa v[146:147], v71 src0_sel:WORD_1
	v_pk_fma_f32 v[148:149], v[140:141], v[112:113], v[148:149]
	v_pk_fma_f32 v[148:149], v[142:143], v[114:115], v[148:149]
	v_pk_fma_f32 v[148:149], v[144:145], v[116:117], v[148:149]
	v_pk_fma_f32 v[148:149], v[146:147], v[118:119], v[148:149]
	v_add_f32_e32 v173, v148, v149
	v_lshl_add_u32 v4, v87, 7, v0
	global_load_dwordx4 v[68:71], v4, s[40:41]
	v_cndmask_b32_e64 v152, v156, v157, s[34:35]
	v_cndmask_b32_e64 v174, v157, v156, s[34:35]
	v_cndmask_b32_e64 v153, v158, v159, s[34:35]
	v_cndmask_b32_e64 v175, v159, v158, s[34:35]
	v_cndmask_b32_e64 v154, v160, v161, s[34:35]
	v_cndmask_b32_e64 v176, v161, v160, s[34:35]
	v_cndmask_b32_e64 v155, v162, v163, s[34:35]
	v_cndmask_b32_e64 v177, v163, v162, s[34:35]
	v_add_f32_dpp v156, v174, v152 quad_perm:[1,0,3,2] row_mask:0xf bank_mask:0xf
	v_add_f32_dpp v157, v175, v153 quad_perm:[1,0,3,2] row_mask:0xf bank_mask:0xf
	v_add_f32_dpp v158, v176, v154 quad_perm:[1,0,3,2] row_mask:0xf bank_mask:0xf
	v_add_f32_dpp v159, v177, v155 quad_perm:[1,0,3,2] row_mask:0xf bank_mask:0xf
	v_cndmask_b32_e64 v152, v166, v167, s[34:35]
	v_cndmask_b32_e64 v174, v167, v166, s[34:35]
	v_cndmask_b32_e64 v153, v168, v169, s[34:35]
	v_cndmask_b32_e64 v175, v169, v168, s[34:35]
	v_cndmask_b32_e64 v154, v170, v171, s[34:35]
	v_cndmask_b32_e64 v176, v171, v170, s[34:35]
	v_cndmask_b32_e64 v155, v172, v173, s[34:35]
	v_cndmask_b32_e64 v177, v173, v172, s[34:35]
	v_add_f32_dpp v160, v174, v152 quad_perm:[1,0,3,2] row_mask:0xf bank_mask:0xf
	v_add_f32_dpp v161, v175, v153 quad_perm:[1,0,3,2] row_mask:0xf bank_mask:0xf
	v_add_f32_dpp v162, v176, v154 quad_perm:[1,0,3,2] row_mask:0xf bank_mask:0xf
	v_add_f32_dpp v163, v177, v155 quad_perm:[1,0,3,2] row_mask:0xf bank_mask:0xf
	v_cndmask_b32_e64 v152, v156, v157, s[48:49]
	v_cndmask_b32_e64 v174, v157, v156, s[48:49]
	v_cndmask_b32_e64 v153, v158, v159, s[48:49]
	v_cndmask_b32_e64 v175, v159, v158, s[48:49]
	v_cndmask_b32_e64 v154, v160, v161, s[48:49]
	v_cndmask_b32_e64 v176, v161, v160, s[48:49]
	v_cndmask_b32_e64 v155, v162, v163, s[48:49]
	v_cndmask_b32_e64 v177, v163, v162, s[48:49]
	v_add_f32_dpp v156, v174, v152 quad_perm:[2,3,0,1] row_mask:0xf bank_mask:0xf
	v_add_f32_dpp v157, v175, v153 quad_perm:[2,3,0,1] row_mask:0xf bank_mask:0xf
	v_add_f32_dpp v158, v176, v154 quad_perm:[2,3,0,1] row_mask:0xf bank_mask:0xf
	v_add_f32_dpp v159, v177, v155 quad_perm:[2,3,0,1] row_mask:0xf bank_mask:0xf
	v_mov_b64_e32 v[216:217], v[218:219]
	v_mov_b64_e32 v[218:219], v[220:221]
	v_mov_b64_e32 v[220:221], v[222:223]
	v_mov_b64_e32 v[222:223], v[224:225]
	v_mov_b64_e32 v[224:225], v[226:227]
	v_mov_b64_e32 v[226:227], v[232:233]
	v_mov_b64_e32 v[232:233], v[234:235]
	v_cndmask_b32_e64 v152, v156, v157, s[50:51]
	v_cndmask_b32_e64 v174, v157, v156, s[50:51]
	v_cndmask_b32_e64 v153, v158, v159, s[50:51]
	v_cndmask_b32_e64 v175, v159, v158, s[50:51]
	v_add_f32_dpp v234, v174, v152 row_shl:4 row_mask:0xf bank_mask:0x5
	v_add_f32_dpp v234, v174, v152 row_shr:4 row_mask:0xf bank_mask:0xa
	v_add_f32_dpp v235, v175, v153 row_shl:4 row_mask:0xf bank_mask:0x5
	v_add_f32_dpp v235, v175, v153 row_shr:4 row_mask:0xf bank_mask:0xa
	s_cmp_eq_u32 s47, 7
	s_cbranch_scc0 .Lpu_b1_nost
	s_bfe_u32 s45, s0, 0x40003
	s_lshl_b32 s45, s45, 20
	s_add_u32 s45, s45, s8
	s_lshr_b32 s46, s0, 7
	s_add_u32 s46, s46, s9
	s_lshl_b32 s46, s46, 24
	s_add_u32 s45, s45, s46
	s_add_u32 s45, s45, 0x20000000
	s_add_u32 s42, s98, s45
	s_addc_u32 s43, s99, 0
	global_store_dwordx4 v2, v[216:219], s[42:43]
	global_store_dwordx4 v2, v[220:223], s[42:43] offset:128
	global_store_dwordx4 v2, v[224:227], s[42:43] offset:256
	global_store_dwordx4 v2, v[232:235], s[42:43] offset:384
	v_lshlrev_b32_e32 v104, 16, v120
	v_and_b32_e32 v105, 0xffff0000, v120
	v_lshlrev_b32_e32 v106, 16, v121
	v_and_b32_e32 v107, 0xffff0000, v121
	v_lshlrev_b32_e32 v108, 16, v122
	v_and_b32_e32 v109, 0xffff0000, v122
	v_lshlrev_b32_e32 v110, 16, v123
	v_and_b32_e32 v111, 0xffff0000, v123
	v_lshlrev_b32_e32 v112, 16, v124
	v_and_b32_e32 v113, 0xffff0000, v124
	v_lshlrev_b32_e32 v114, 16, v125
	v_and_b32_e32 v115, 0xffff0000, v125
	v_lshlrev_b32_e32 v116, 16, v126
	v_and_b32_e32 v117, 0xffff0000, v126
	v_lshlrev_b32_e32 v118, 16, v127
	v_and_b32_e32 v119, 0xffff0000, v127

; #define LAS __attribute__((address_space(3)))
; #define LDS_WAIT() asm volatile("s_waitcnt lgkmcnt(0)" ::: "memory")
; template <bool WIN>
; DI void transpose_item(const float* W, int K, int Nsrc, bf16_t* WT, int k0, int n0, LAS float* scr, int lane, const float* gk = nullptr) {
;     const int nd = n0 + (lane & 31);
;     const int ns = WIN ? win_srccol(nd) : nd;
; #pragma unroll 8
;     for (int i = 0; i < 32; ++i) { const int kk = 2 * i + (lane >> 5); scr[kk * 33 + (lane & 31)] = (ns >= 0 ? W[(size_t)(k0 + kk) * Nsrc + ns] : 0.f) * (gk ? gk[k0 + kk] : 1.f); }
;     LDS_WAIT();
;     const int c = lane & 7;
; #pragma unroll
;     for (int j = 0; j < 4; ++j) { const int n = (lane >> 3) + 8 * j; const LAS float* s = scr + (8 * c) * 33 + n;
;         u32x4 o; o.x = pk2(s[0 * 33], s[1 * 33]); o.y = pk2(s[2 * 33], s[3 * 33]); o.z = pk2(s[4 * 33], s[5 * 33]); o.w = pk2(s[6 * 33], s[7 * 33]);
;         *(u32x4*)(WT + (size_t)(n0 + n) * K + k0 + 8 * c) = o; }
;     LDS_WAIT();
; }
; template <bool WIN>
; DI void transpose_matrix(const float* W, int K, int Nsrc, int Ndst, bf16_t* WT, LAS float* scr, int lane, int gw, int NGW, const float* gk = nullptr) {
;     const int nblk = Ndst / 32, nitems = (K / 64) * nblk;
;     for (int it = gw; it < nitems; it += NGW) transpose_item<WIN>(W, K, Nsrc, WT, 64 * (it / nblk), 32 * (it % nblk), scr, lane, gk);
; }
; DI void phase_prologue(const Args& a, LAS unsigned char* lds) {
;     ...
;     for (int l = 0; l < NLAYER; ++l) {
;         transpose_matrix<true>(a.w_in + (size_t)l * D * NPROJ, D, NPROJ, NP, (bf16_t*)(ws + WS_WIN) + (size_t)l * NP * D, scr, lane, gw, NGW);
;         transpose_matrix<false>(a.w_out + (size_t)l * D * D, D, D, D, (bf16_t*)(ws + WS_WOUT) + (size_t)l * D * D, scr, lane, gw, NGW);
;         transpose_matrix<false>(a.peer_wq + (size_t)l * D * D, D, D, D, (bf16_t*)(ws + WS_WQ) + (size_t)l * D * D, scr, lane, gw, NGW, a.ffn_norm + (size_t)l * D);
;         transpose_matrix<false>(a.cmp_w1_k + (size_t)l * 2048 * 128, 2048, 128, 128, (bf16_t*)(ws + WS_CW1) + (size_t)(l * 2 + 0) * 128 * 2048, scr, lane, gw, NGW);
;         transpose_matrix<false>(a.cmp_w1_v + (size_t)l * 2048 * 128, 2048, 128, 128, (bf16_t*)(ws + WS_CW1) + (size_t)(l * 2 + 1) * 128 * 2048, scr, lane, gw, NGW);
;     }
.LBB0_504:
	s_or_b64 exec, exec, s[0:1]
	v_readlane_b32 s0, v252, 5
	v_readlane_b32 s1, v252, 6
	s_load_dword s24, s[0:1], 0x0
	v_and_b32_e32 v2, 63, v185
	v_lshrrev_b32_e32 v3, 6, v185
	v_and_b32_e32 v4, 7, v2
	v_lshrrev_b32_e32 v5, 3, v2
	v_readfirstlane_b32 s52, v3
	v_readlane_b32 s53, v252, 0
	s_mul_i32 s54, s52, 0x2400
	v_mul_u32_u24_e32 v6, 0x90, v5
	v_lshl_add_u32 v6, v4, 4, v6
	v_add_u32_e32 v6, s54, v6
	v_lshlrev_b32_e32 v7, 4, v4
	v_mul_u32_u24_e32 v8, 0x480, v4
	v_lshl_add_u32 v8, v5, 2, v8
	v_add_u32_e32 v8, s54, v8
	v_lshlrev_b32_e32 v9, 12, v5
	v_lshl_add_u32 v9, v4, 4, v9
	v_lshlrev_b32_e32 v10, 5, v4
	v_cmp_gt_u32_e64 s[60:61], 4, v4
	s_lshl_b32 s53, s53, 3
	s_add_u32 s53, s53, s52
	s_mov_b32 s38, 0
.Ltp_job:
	s_and_b32 s39, s38, 1
	s_lshr_b32 s48, s38, 1
	s_mov_b64 s[50:51], 0
	s_cmp_eq_u32 s48, 0
	s_cbranch_scc0 .Ltp_k1
	s_mul_i32 s55, s39, 0x1860000
	s_add_u32 s40, s80, s55
	s_addc_u32 s41, s81, 0
	s_movk_i32 s42, 0x30c0
	s_movk_i32 s43, 104
	s_movk_i32 s44, 3328
	s_movk_i32 s45, 20165
	s_mul_i32 s55, s39, 0xd00000
	s_add_u32 s46, s98, s55
	s_addc_u32 s47, s99, 0
	s_branch .Ltp_go
.Ltp_k1:
	s_cmp_eq_u32 s48, 1
	s_cbranch_scc0 .Ltp_k2
	s_lshl_b32 s55, s39, 24
	s_add_u32 s40, s68, s55
	s_addc_u32 s41, s69, 0
	s_movk_i32 s42, 0x2000
	s_movk_i32 s43, 64
	s_movk_i32 s44, 2048
	s_mov_b32 s45, 0x8000
	s_lshl_b32 s55, s39, 23
	s_add_u32 s55, s55, 0x1c00000
	s_add_u32 s46, s98, s55
	s_addc_u32 s47, s99, 0
	s_branch .Ltp_go
.Ltp_k2:
	s_cmp_eq_u32 s48, 2
	s_cbranch_scc0 .Ltp_k3
	s_lshl_b32 s55, s39, 24
	s_add_u32 s40, s72, s55
	s_addc_u32 s41, s73, 0
	s_movk_i32 s42, 0x2000
	s_movk_i32 s43, 64
	s_movk_i32 s44, 2048
	s_mov_b32 s45, 0x8000
	s_lshl_b32 s55, s39, 23
	s_add_u32 s55, s55, 0x2e00000
	s_add_u32 s46, s98, s55
	s_addc_u32 s47, s99, 0
	s_lshl_b32 s55, s39, 13
	s_add_u32 s50, s70, s55
	s_addc_u32 s51, s71, 0
	s_branch .Ltp_go
.Ltp_k3:
	s_cmp_eq_u32 s48, 3
	s_cselect_b32 s40, s84, s90
	s_cselect_b32 s41, s85, s91
	s_cselect_b32 s56, 0, 1
	s_lshl_b32 s55, s39, 20
	s_add_u32 s40, s40, s55
	s_addc_u32 s41, s41, 0
	s_movk_i32 s42, 0x200
	s_movk_i32 s43, 4
	s_movk_i32 s44, 128
	s_mov_b32 s45, 0x80000
	s_lshl_b32 s55, s39, 1
	s_add_u32 s55, s55, s56
	s_lshl_b32 s55, s55, 19
	s_add_u32 s55, s55, 0x4000000
	s_add_u32 s46, s98, s55
	s_addc_u32 s47, s99, 0
.Ltp_go:
	s_mov_b32 s49, s53
.Ltp_item:
	s_cmp_ge_u32 s49, s44
	s_cbranch_scc1 .Ltp_nextjob
	s_mul_i32 s55, s49, s45
	s_lshr_b32 s55, s55, 21
	s_mul_i32 s56, s55, s43
	s_sub_u32 s56, s49, s56
	s_lshl_b32 s57, s56, 5
	s_mov_b32 s58, s57
	s_mov_b32 s100, 0
	s_cmp_lg_u32 s48, 0
	s_cbranch_scc1 .Ltp_nomap
	s_cmpk_lt_u32 s57, 0x400
	s_cbranch_scc1 .Ltp_nomap
	s_add_u32 s58, s57, 816
	s_cmpk_lt_u32 s57, 0x800
	s_cbranch_scc1 .Ltp_nomap
	s_sub_u32 s58, s57, 0x400
	s_cmpk_lt_u32 s57, 0xb00
	s_cbranch_scc1 .Ltp_nomap
	s_add_u32 s58, s57, 48
	s_cmpk_lt_u32 s57, 0xc00
	s_cbranch_scc1 .Ltp_nomap
	s_sub_u32 s58, s57, 0x500
	s_cmpk_lt_u32 s57, 0xc20
	s_cbranch_scc1 .Ltp_nomap
	s_mov_b32 s100, 1
	s_cmpk_lt_u32 s57, 0xc40
	s_cbranch_scc1 .Ltp_nomap
	s_mov_b32 s100, 2
.Ltp_nomap:
	s_lshl_b32 s101, s55, 6
	s_mul_i32 s16, s101, s42
	s_lshl_b32 s17, s58, 2
	s_add_u32 s16, s16, s17
	s_add_u32 s18, s40, s16
	s_addc_u32 s19, s41, 0
	v_mul_lo_u32 v11, v5, s42
	v_add_u32_e32 v11, v11, v7
	s_lshl_b32 s17, s42, 3
	s_lshl_b32 s22, s57, 12
	s_lshl_b32 s23, s101, 1
	s_add_u32 s22, s22, s23
	s_add_u32 s22, s46, s22
	s_addc_u32 s23, s47, 0
	s_cmp_eq_u32 s100, 2
	s_cbranch_scc1 .Ltp_zero
	global_load_dwordx4 v[16:19], v11, s[18:19]
	s_add_u32 s18, s18, s17
	s_addc_u32 s19, s19, 0
	global_load_dwordx4 v[20:23], v11, s[18:19]
	s_add_u32 s18, s18, s17
	s_addc_u32 s19, s19, 0
	global_load_dwordx4 v[24:27], v11, s[18:19]
	s_add_u32 s18, s18, s17
	s_addc_u32 s19, s19, 0
	global_load_dwordx4 v[28:31], v11, s[18:19]
	s_add_u32 s18, s18, s17
	s_addc_u32 s19, s19, 0
	global_load_dwordx4 v[32:35], v11, s[18:19]
	s_add_u32 s18, s18, s17
	s_addc_u32 s19, s19, 0
	global_load_dwordx4 v[36:39], v11, s[18:19]
	s_add_u32 s18, s18, s17
	s_addc_u32 s19, s19, 0
	global_load_dwordx4 v[40:43], v11, s[18:19]
	s_add_u32 s18, s18, s17
	s_addc_u32 s19, s19, 0
	global_load_dwordx4 v[44:47], v11, s[18:19]
	s_cmp_lg_u64 s[50:51], 0
	s_cbranch_scc0 .Ltp_nogk1
	s_lshl_b32 s16, s101, 2
	s_add_u32 s18, s50, s16
	s_addc_u32 s19, s51, 0
	global_load_dwordx4 v[48:51], v10, s[18:19]
	global_load_dwordx4 v[52:55], v10, s[18:19] offset:16
; #define LAS __attribute__((address_space(3)))
; #define LDS_WAIT() asm volatile("s_waitcnt lgkmcnt(0)" ::: "memory")
; DI unsigned pk2(float lo, float hi) { const f32x2 v = {lo, hi}; return __builtin_bit_cast(unsigned, __builtin_convertvector(v, bf16v2)); }
; template <bool WIN>
; DI void transpose_item(const float* W, int K, int Nsrc, bf16_t* WT, int k0, int n0, LAS float* scr, int lane, const float* gk = nullptr) {
;     ...
;     for (int i = 0; i < 32; ++i) { const int kk = 2 * i + (lane >> 5); scr[kk * 33 + (lane & 31)] = (ns >= 0 ? W[(size_t)(k0 + kk) * Nsrc + ns] : 0.f) * (gk ? gk[k0 + kk] : 1.f); }
;     LDS_WAIT();
;     const int c = lane & 7;
; #pragma unroll
;     for (int j = 0; j < 4; ++j) { const int n = (lane >> 3) + 8 * j; const LAS float* s = scr + (8 * c) * 33 + n;
;         u32x4 o; o.x = pk2(s[0 * 33], s[1 * 33]); o.y = pk2(s[2 * 33], s[3 * 33]); o.z = pk2(s[4 * 33], s[5 * 33]); o.w = pk2(s[6 * 33], s[7 * 33]);
;         *(u32x4*)(WT + (size_t)(n0 + n) * K + k0 + 8 * c) = o; }
;     LDS_WAIT();
.Ltp_nogk1:
	s_waitcnt vmcnt(0)
	s_cmp_eq_u32 s100, 1
	s_cbranch_scc0 .Ltp_full
	v_cndmask_b32_e64 v16, 0, v16, s[60:61]
	v_cndmask_b32_e64 v17, 0, v17, s[60:61]
	v_cndmask_b32_e64 v18, 0, v18, s[60:61]
	v_cndmask_b32_e64 v19, 0, v19, s[60:61]
	v_cndmask_b32_e64 v20, 0, v20, s[60:61]
	v_cndmask_b32_e64 v21, 0, v21, s[60:61]
	v_cndmask_b32_e64 v22, 0, v22, s[60:61]
	v_cndmask_b32_e64 v23, 0, v23, s[60:61]
	v_cndmask_b32_e64 v24, 0, v24, s[60:61]
	v_cndmask_b32_e64 v25, 0, v25, s[60:61]
	v_cndmask_b32_e64 v26, 0, v26, s[60:61]
	v_cndmask_b32_e64 v27, 0, v27, s[60:61]
	v_cndmask_b32_e64 v28, 0, v28, s[60:61]
	v_cndmask_b32_e64 v29, 0, v29, s[60:61]
	v_cndmask_b32_e64 v30, 0, v30, s[60:61]
	v_cndmask_b32_e64 v31, 0, v31, s[60:61]
	v_cndmask_b32_e64 v32, 0, v32, s[60:61]
	v_cndmask_b32_e64 v33, 0, v33, s[60:61]
	v_cndmask_b32_e64 v34, 0, v34, s[60:61]
	v_cndmask_b32_e64 v35, 0, v35, s[60:61]
	v_cndmask_b32_e64 v36, 0, v36, s[60:61]
	v_cndmask_b32_e64 v37, 0, v37, s[60:61]
	v_cndmask_b32_e64 v38, 0, v38, s[60:61]
	v_cndmask_b32_e64 v39, 0, v39, s[60:61]
	v_cndmask_b32_e64 v40, 0, v40, s[60:61]
	v_cndmask_b32_e64 v41, 0, v41, s[60:61]
	v_cndmask_b32_e64 v42, 0, v42, s[60:61]
	v_cndmask_b32_e64 v43, 0, v43, s[60:61]
	v_cndmask_b32_e64 v44, 0, v44, s[60:61]
	v_cndmask_b32_e64 v45, 0, v45, s[60:61]
	v_cndmask_b32_e64 v46, 0, v46, s[60:61]
	v_cndmask_b32_e64 v47, 0, v47, s[60:61]
.Ltp_full:
	ds_write_b128 v6, v[16:19] offset:0
	ds_write_b128 v6, v[20:23] offset:1152
	ds_write_b128 v6, v[24:27] offset:2304
	ds_write_b128 v6, v[28:31] offset:3456
	ds_write_b128 v6, v[32:35] offset:4608
	ds_write_b128 v6, v[36:39] offset:5760
	ds_write_b128 v6, v[40:43] offset:6912
	ds_write_b128 v6, v[44:47] offset:8064
	s_waitcnt lgkmcnt(0)
	ds_read_b32 v56, v8 offset:0
	ds_read_b32 v57, v8 offset:144
	ds_read_b32 v58, v8 offset:288
	ds_read_b32 v59, v8 offset:432
	ds_read_b32 v60, v8 offset:576
	ds_read_b32 v61, v8 offset:720
	ds_read_b32 v62, v8 offset:864
	ds_read_b32 v63, v8 offset:1008
	s_waitcnt lgkmcnt(0)
	s_cmp_lg_u64 s[50:51], 0
	s_cbranch_scc0 .Ltp_nogk2_0
	v_pk_mul_f32 v[56:57], v[56:57], v[48:49]
	v_pk_mul_f32 v[58:59], v[58:59], v[50:51]
	v_pk_mul_f32 v[60:61], v[60:61], v[52:53]
	v_pk_mul_f32 v[62:63], v[62:63], v[54:55]
.Ltp_nogk2_0:
	v_cvt_pk_bf16_f32 v12, v56, v57
	v_cvt_pk_bf16_f32 v13, v58, v59
	v_cvt_pk_bf16_f32 v14, v60, v61
	v_cvt_pk_bf16_f32 v15, v62, v63
	global_store_dwordx4 v9, v[12:15], s[22:23]
	s_add_u32 s22, s22, 0x8000
	s_addc_u32 s23, s23, 0
	ds_read_b32 v56, v8 offset:32
	ds_read_b32 v57, v8 offset:176
	ds_read_b32 v58, v8 offset:320
	ds_read_b32 v59, v8 offset:464
	ds_read_b32 v60, v8 offset:608
	ds_read_b32 v61, v8 offset:752
	ds_read_b32 v62, v8 offset:896
	ds_read_b32 v63, v8 offset:1040
	s_waitcnt lgkmcnt(0)
	s_cmp_lg_u64 s[50:51], 0
	s_cbranch_scc0 .Ltp_nogk2_1
	v_pk_mul_f32 v[56:57], v[56:57], v[48:49]
	v_pk_mul_f32 v[58:59], v[58:59], v[50:51]
	v_pk_mul_f32 v[60:61], v[60:61], v[52:53]
	v_pk_mul_f32 v[62:63], v[62:63], v[54:55]
.Ltp_nogk2_1:
	v_cvt_pk_bf16_f32 v12, v56, v57
	v_cvt_pk_bf16_f32 v13, v58, v59
	v_cvt_pk_bf16_f32 v14, v60, v61
	v_cvt_pk_bf16_f32 v15, v62, v63
	global_store_dwordx4 v9, v[12:15], s[22:23]
	s_add_u32 s22, s22, 0x8000
	s_addc_u32 s23, s23, 0
	ds_read_b32 v56, v8 offset:64
	ds_read_b32 v57, v8 offset:208
	ds_read_b32 v58, v8 offset:352
	ds_read_b32 v59, v8 offset:496
	ds_read_b32 v60, v8 offset:640
	ds_read_b32 v61, v8 offset:784
	ds_read_b32 v62, v8 offset:928
	ds_read_b32 v63, v8 offset:1072
	s_waitcnt lgkmcnt(0)
	s_cmp_lg_u64 s[50:51], 0
	s_cbranch_scc0 .Ltp_nogk2_2
	v_pk_mul_f32 v[56:57], v[56:57], v[48:49]
	v_pk_mul_f32 v[58:59], v[58:59], v[50:51]
	v_pk_mul_f32 v[60:61], v[60:61], v[52:53]
	v_pk_mul_f32 v[62:63], v[62:63], v[54:55]
.Ltp_nogk2_2:
	v_cvt_pk_bf16_f32 v12, v56, v57
	v_cvt_pk_bf16_f32 v13, v58, v59
	v_cvt_pk_bf16_f32 v14, v60, v61
	v_cvt_pk_bf16_f32 v15, v62, v63
	global_store_dwordx4 v9, v[12:15], s[22:23]
	s_add_u32 s22, s22, 0x8000
	s_addc_u32 s23, s23, 0
	ds_read_b32 v56, v8 offset:96
	ds_read_b32 v57, v8 offset:240
	ds_read_b32 v58, v8 offset:384
	ds_read_b32 v59, v8 offset:528
	ds_read_b32 v60, v8 offset:672
	ds_read_b32 v61, v8 offset:816
	ds_read_b32 v62, v8 offset:960
	ds_read_b32 v63, v8 offset:1104
	s_waitcnt lgkmcnt(0)
	s_cmp_lg_u64 s[50:51], 0
	s_cbranch_scc0 .Ltp_nogk2_3
	v_pk_mul_f32 v[56:57], v[56:57], v[48:49]
	v_pk_mul_f32 v[58:59], v[58:59], v[50:51]
	v_pk_mul_f32 v[60:61], v[60:61], v[52:53]
	v_pk_mul_f32 v[62:63], v[62:63], v[54:55]
.Ltp_nogk2_3:
	v_cvt_pk_bf16_f32 v12, v56, v57
	v_cvt_pk_bf16_f32 v13, v58, v59
	v_cvt_pk_bf16_f32 v14, v60, v61
	v_cvt_pk_bf16_f32 v15, v62, v63
	global_store_dwordx4 v9, v[12:15], s[22:23]
	s_branch .Ltp_next
.Ltp_zero:
	v_mov_b32_e32 v12, 0
	v_mov_b32_e32 v13, 0
	v_mov_b32_e32 v14, 0
	v_mov_b32_e32 v15, 0
	global_store_dwordx4 v9, v[12:15], s[22:23]
	s_add_u32 s22, s22, 0x8000
	s_addc_u32 s23, s23, 0
	global_store_dwordx4 v9, v[12:15], s[22:23]
	s_add_u32 s22, s22, 0x8000
	s_addc_u32 s23, s23, 0
	global_store_dwordx4 v9, v[12:15], s[22:23]
	s_add_u32 s22, s22, 0x8000
	s_addc_u32 s23, s23, 0
	global_store_dwordx4 v9, v[12:15], s[22:23]
.Ltp_next:
	s_add_u32 s49, s49, 0x800
	s_branch .Ltp_item
.Ltp_nextjob:
	s_add_u32 s38, s38, 1
	s_cmp_lt_u32 s38, 10
	s_cbranch_scc1 .Ltp_job
	s_waitcnt vmcnt(0) lgkmcnt(0)
	s_lshl_b32 s8, s24, 3
